# tile-header fast path when group size is 8; removed canonicalizing v_max before relu in EpiA
# baseline (speedup 1.0000x reference)
.Lh_noov:
	s_waitcnt lgkmcnt(0)
	v_mov_b64_e32 v[0:1], s[60:61]
	v_cmp_ge_i64_e32 vcc, s[40:41], v[0:1]
	v_cmp_lt_i64_e64 s[42:43], s[40:41], v[0:1]
	s_cbranch_vccnz .LBB0_405
	s_ashr_i32 s10, s40, 31
	s_lshr_b32 s10, s10, 29
	s_add_i32 s10, s40, s10
	s_ashr_i32 s41, s10, 3
	s_and_b32 s10, s10, -8
	s_sub_i32 s10, s40, s10
	s_lshr_b32 s40, s10, 31
	s_add_i32 s40, s54, s40
	s_mul_i32 s10, s40, s10
	s_add_i32 s10, s10, s41
	s_abs_i32 s41, s10
	s_mul_hi_u32 s48, s41, s58
	s_mul_i32 s49, s48, s46
	s_ashr_i32 s40, s10, 31
	s_sub_i32 s41, s41, s49
	s_xor_b32 s40, s40, s55
	s_add_i32 s49, s48, 1
	s_sub_i32 s52, s41, s46
	s_cmp_ge_u32 s41, s46
	s_cselect_b32 s48, s49, s48
	s_cselect_b32 s41, s52, s41
	s_add_i32 s49, s48, 1
	s_cmp_ge_u32 s41, s46
	s_cselect_b32 s41, s49, s48
	s_xor_b32 s41, s41, s40
	s_sub_i32 s40, s41, s40
	s_lshl_b32 s41, s40, 3
	s_sub_i32 s48, s11, s41
	s_min_i32 s48, s48, 8
	s_mul_i32 s40, s40, s31
	s_sub_i32 s10, s10, s40
	s_cmp_eq_u32 s48, 8
	s_cbranch_scc0 .Lslow404
	s_lshr_b32 s59, s10, 3
	s_and_b32 s10, s10, 7
	v_readlane_b32 s52, v252, 10
	v_readlane_b32 s53, v252, 11
	s_add_i32 s88, s10, s41
	s_branch .LBB0_405
.Lslow404:
	s_abs_i32 s49, s48
	v_cvt_f32_u32_e32 v0, s49
	s_sub_i32 s53, 0, s49
	v_rcp_iflag_f32_e32 v0, v0
	s_abs_i32 s52, s10
	s_xor_b32 s40, s10, s48
	s_ashr_i32 s40, s40, 31
	v_mul_f32_e32 v0, 0x4f7ffffe, v0
	v_cvt_u32_f32_e32 v0, v0
	s_nop 0
	v_readfirstlane_b32 s59, v0
	s_mul_i32 s53, s53, s59
	s_mul_hi_u32 s53, s59, s53
	s_add_i32 s59, s59, s53
	s_mul_hi_u32 s53, s52, s59
	s_mul_i32 s59, s53, s49
	s_sub_i32 s52, s52, s59
	s_add_i32 s59, s53, 1
	s_sub_i32 s80, s52, s49
	s_cmp_ge_u32 s52, s49
	s_cselect_b32 s53, s59, s53
	s_cselect_b32 s52, s80, s52
	s_add_i32 s59, s53, 1
	s_cmp_ge_u32 s52, s49
	s_cselect_b32 s49, s59, s53
	s_xor_b32 s49, s49, s40
	s_sub_i32 s59, s49, s40
	s_mul_i32 s40, s59, s48
	v_readlane_b32 s52, v252, 10
	s_sub_i32 s10, s10, s40
	v_readlane_b32 s53, v252, 11
	s_add_i32 s88, s10, s41

.LBB0_551:
	s_add_i32 s9, s9, 1
	v_readlane_b32 s10, v255, 15
	s_mul_i32 s28, s9, s10
	v_readlane_b32 s10, v255, 14
	s_mul_hi_u32 s29, s9, s10
	s_add_i32 s29, s29, s28
	s_mul_i32 s28, s9, s10
	v_readlane_b32 s34, v255, 8
	v_readlane_b32 s35, v255, 9
	s_add_u32 s28, s28, s34
	s_addc_u32 s29, s29, s35
	v_mov_b64_e32 v[0:1], s[60:61]
	v_cmp_ge_i64_e32 vcc, s[28:29], v[0:1]
	v_cmp_lt_i64_e64 s[42:43], s[28:29], v[0:1]
	s_cbranch_vccnz .LBB0_553
	s_ashr_i32 s6, s28, 31
	s_lshr_b32 s6, s6, 29
	s_add_i32 s6, s28, s6
	s_ashr_i32 s29, s6, 3
	s_and_b32 s6, s6, -8
	s_sub_i32 s6, s28, s6
	s_lshr_b32 s28, s6, 31
	s_add_i32 s28, s21, s28
	s_mul_i32 s6, s28, s6
	s_add_i32 s6, s6, s29
	s_abs_i32 s29, s6
	s_mul_hi_u32 s34, s29, s55
	s_mul_i32 s35, s34, s59
	s_ashr_i32 s28, s6, 31
	s_sub_i32 s29, s29, s35
	s_xor_b32 s28, s28, s54
	s_add_i32 s35, s34, 1
	s_sub_i32 s40, s29, s59
	s_cmp_ge_u32 s29, s59
	s_cselect_b32 s34, s35, s34
	s_cselect_b32 s29, s40, s29
	s_add_i32 s35, s34, 1
	s_cmp_ge_u32 s29, s59
	s_cselect_b32 s29, s35, s34
	s_xor_b32 s29, s29, s28
	s_sub_i32 s28, s29, s28
	s_lshl_b32 s29, s28, 3
	s_sub_i32 s34, s11, s29
	s_min_i32 s34, s34, 8
	s_mul_i32 s28, s28, s58
	s_sub_i32 s28, s6, s28
	s_cmp_eq_u32 s34, 8
	s_cbranch_scc0 .Lslow552
	s_lshr_b32 s6, s28, 3
	s_and_b32 s28, s28, 7
	s_add_i32 s48, s28, s29
	s_branch .LBB0_553
.Lslow552:
	s_abs_i32 s35, s34
	v_cvt_f32_u32_e32 v0, s35
	s_sub_i32 s41, 0, s35
	v_rcp_iflag_f32_e32 v0, v0
	s_abs_i32 s40, s28
	s_xor_b32 s6, s28, s34
	s_ashr_i32 s6, s6, 31
	v_mul_f32_e32 v0, 0x4f7ffffe, v0
	v_cvt_u32_f32_e32 v0, v0
	s_nop 0
	v_readfirstlane_b32 s48, v0
	s_mul_i32 s41, s41, s48
	s_mul_hi_u32 s41, s48, s41
	s_add_i32 s48, s48, s41
	s_mul_hi_u32 s41, s40, s48
	s_mul_i32 s48, s41, s35
	s_sub_i32 s40, s40, s48
	s_add_i32 s48, s41, 1
	s_sub_i32 s49, s40, s35
	s_cmp_ge_u32 s40, s35
	s_cselect_b32 s41, s48, s41
	s_cselect_b32 s40, s49, s40
	s_add_i32 s48, s41, 1
	s_cmp_ge_u32 s40, s35
	s_cselect_b32 s35, s48, s41
	s_xor_b32 s35, s35, s6
	s_sub_i32 s6, s35, s6
	s_mul_i32 s34, s6, s34
	s_sub_i32 s28, s28, s34
	s_add_i32 s48, s28, s29

.LBB0_574:
	v_and_or_b32 v146, v208, 64, v157
	v_lshlrev_b32_e32 v175, 2, v146
	ds_bpermute_b32 v164, v175, v176
	v_cndmask_b32_e64 v146, 0, 1, s[88:89]
	v_cmp_ne_u32_e64 s[42:43], 1, v146
	s_andn2_b64 vcc, exec, s[88:89]
	s_waitcnt vmcnt(0) lgkmcnt(0)
	v_pk_fma_f32 v[148:149], v[140:141], v[164:165], v[88:89] op_sel_hi:[1,0,1]
	v_pk_fma_f32 v[146:147], v[138:139], v[164:165], v[86:87] op_sel_hi:[1,0,1]
	v_pk_fma_f32 v[140:141], v[144:145], v[164:165], v[84:85] op_sel_hi:[1,0,1]
	v_pk_fma_f32 v[138:139], v[142:143], v[164:165], v[82:83] op_sel_hi:[1,0,1]
	s_cbranch_vccnz .LBB0_576
	v_max_f32_e32 v142, 0, v146
	v_max_f32_e32 v138, 0, v138
	v_max_f32_e32 v143, 0, v147
	v_max_f32_e32 v139, 0, v139
	v_max_f32_e32 v144, 0, v148
	v_max_f32_e32 v140, 0, v140
	v_max_f32_e32 v145, 0, v149
	v_max_f32_e32 v141, 0, v141
	v_pk_mul_f32 v[146:147], v[142:143], v[142:143]
	v_pk_mul_f32 v[148:149], v[144:145], v[144:145]
	v_pk_mul_f32 v[138:139], v[138:139], v[138:139]
	v_pk_mul_f32 v[140:141], v[140:141], v[140:141]

.LBB0_579:
	v_mov_b32_e32 v165, v164
	v_mov_b32_e32 v138, v164
	v_mov_b32_e32 v139, v164
	v_pk_fma_f32 v[136:137], v[136:137], v[138:139], v[72:73]
	v_pk_fma_f32 v[134:135], v[134:135], v[164:165], v[70:71]
	v_pk_fma_f32 v[132:133], v[132:133], v[138:139], v[68:69]
	s_and_b64 vcc, exec, s[42:43]
	v_pk_fma_f32 v[130:131], v[130:131], v[164:165], v[66:67]
	s_cbranch_vccnz .LBB0_581
	v_max_f32_e32 v134, 0, v134
	v_max_f32_e32 v130, 0, v130
	v_max_f32_e32 v135, 0, v135
	v_max_f32_e32 v131, 0, v131
	v_max_f32_e32 v136, 0, v136
	v_max_f32_e32 v132, 0, v132
	v_max_f32_e32 v137, 0, v137
	v_max_f32_e32 v133, 0, v133
	v_pk_mul_f32 v[134:135], v[134:135], v[134:135]
	v_pk_mul_f32 v[136:137], v[136:137], v[136:137]
	v_pk_mul_f32 v[130:131], v[130:131], v[130:131]
	v_pk_mul_f32 v[132:133], v[132:133], v[132:133]

.LBB0_584:
	ds_bpermute_b32 v130, v175, v176 offset:64
	s_and_b64 vcc, exec, s[42:43]
	s_waitcnt lgkmcnt(0)
	v_pk_fma_f32 v[128:129], v[128:129], v[130:131], v[88:89] op_sel_hi:[1,0,1]
	v_pk_fma_f32 v[126:127], v[126:127], v[130:131], v[86:87] op_sel_hi:[1,0,1]
	v_pk_fma_f32 v[124:125], v[124:125], v[130:131], v[84:85] op_sel_hi:[1,0,1]
	v_pk_fma_f32 v[122:123], v[122:123], v[130:131], v[82:83] op_sel_hi:[1,0,1]
	s_cbranch_vccnz .LBB0_586
	v_max_f32_e32 v126, 0, v126
	v_max_f32_e32 v122, 0, v122
	v_max_f32_e32 v127, 0, v127
	v_max_f32_e32 v123, 0, v123
	v_max_f32_e32 v128, 0, v128
	v_max_f32_e32 v124, 0, v124
	v_max_f32_e32 v129, 0, v129
	v_max_f32_e32 v125, 0, v125
	v_pk_mul_f32 v[126:127], v[126:127], v[126:127]
	v_pk_mul_f32 v[128:129], v[128:129], v[128:129]
	v_pk_mul_f32 v[122:123], v[122:123], v[122:123]
	v_pk_mul_f32 v[124:125], v[124:125], v[124:125]

.LBB0_589:
	v_mov_b32_e32 v131, v130
	v_mov_b32_e32 v122, v130
	v_mov_b32_e32 v123, v130
	v_pk_fma_f32 v[120:121], v[120:121], v[122:123], v[72:73]
	v_pk_fma_f32 v[118:119], v[118:119], v[130:131], v[70:71]
	v_pk_fma_f32 v[116:117], v[116:117], v[122:123], v[68:69]
	s_and_b64 vcc, exec, s[42:43]
	v_pk_fma_f32 v[114:115], v[114:115], v[130:131], v[66:67]
	s_cbranch_vccnz .LBB0_591
	v_max_f32_e32 v118, 0, v118
	v_max_f32_e32 v114, 0, v114
	v_max_f32_e32 v119, 0, v119
	v_max_f32_e32 v115, 0, v115
	v_max_f32_e32 v120, 0, v120
	v_max_f32_e32 v116, 0, v116
	v_max_f32_e32 v121, 0, v121
	v_max_f32_e32 v117, 0, v117
	v_pk_mul_f32 v[118:119], v[118:119], v[118:119]
	v_pk_mul_f32 v[120:121], v[120:121], v[120:121]
	v_pk_mul_f32 v[114:115], v[114:115], v[114:115]
	v_pk_mul_f32 v[116:117], v[116:117], v[116:117]

.LBB0_594:
	ds_bpermute_b32 v114, v175, v176 offset:128
	s_and_b64 vcc, exec, s[42:43]
	s_waitcnt lgkmcnt(0)
	v_pk_fma_f32 v[112:113], v[112:113], v[114:115], v[88:89] op_sel_hi:[1,0,1]
	v_pk_fma_f32 v[110:111], v[110:111], v[114:115], v[86:87] op_sel_hi:[1,0,1]
	v_pk_fma_f32 v[108:109], v[108:109], v[114:115], v[84:85] op_sel_hi:[1,0,1]
	v_pk_fma_f32 v[106:107], v[106:107], v[114:115], v[82:83] op_sel_hi:[1,0,1]
	s_cbranch_vccnz .LBB0_596
	v_max_f32_e32 v110, 0, v110
	v_max_f32_e32 v106, 0, v106
	v_max_f32_e32 v111, 0, v111
	v_max_f32_e32 v107, 0, v107
	v_max_f32_e32 v112, 0, v112
	v_max_f32_e32 v108, 0, v108
	v_max_f32_e32 v113, 0, v113
	v_max_f32_e32 v109, 0, v109
	v_pk_mul_f32 v[110:111], v[110:111], v[110:111]
	v_pk_mul_f32 v[112:113], v[112:113], v[112:113]
	v_pk_mul_f32 v[106:107], v[106:107], v[106:107]
	v_pk_mul_f32 v[108:109], v[108:109], v[108:109]

.LBB0_599:
	v_mov_b32_e32 v115, v114
	v_mov_b32_e32 v106, v114
	v_mov_b32_e32 v107, v114
	v_pk_fma_f32 v[104:105], v[104:105], v[106:107], v[72:73]
	v_pk_fma_f32 v[102:103], v[102:103], v[114:115], v[70:71]
	v_pk_fma_f32 v[100:101], v[100:101], v[106:107], v[68:69]
	s_and_b64 vcc, exec, s[42:43]
	v_pk_fma_f32 v[98:99], v[98:99], v[114:115], v[66:67]
	s_cbranch_vccnz .LBB0_601
	v_max_f32_e32 v102, 0, v102
	v_max_f32_e32 v98, 0, v98
	v_max_f32_e32 v103, 0, v103
	v_max_f32_e32 v99, 0, v99
	v_max_f32_e32 v104, 0, v104
	v_max_f32_e32 v100, 0, v100
	v_max_f32_e32 v105, 0, v105
	v_max_f32_e32 v101, 0, v101
	v_pk_mul_f32 v[102:103], v[102:103], v[102:103]
	v_pk_mul_f32 v[104:105], v[104:105], v[104:105]
	v_pk_mul_f32 v[98:99], v[98:99], v[98:99]
	v_pk_mul_f32 v[100:101], v[100:101], v[100:101]

.LBB0_604:
	ds_bpermute_b32 v98, v175, v176 offset:192
	s_and_b64 vcc, exec, s[42:43]
	s_waitcnt lgkmcnt(0)
	v_pk_fma_f32 v[96:97], v[96:97], v[98:99], v[88:89] op_sel_hi:[1,0,1]
	v_pk_fma_f32 v[94:95], v[94:95], v[98:99], v[86:87] op_sel_hi:[1,0,1]
	v_pk_fma_f32 v[92:93], v[92:93], v[98:99], v[84:85] op_sel_hi:[1,0,1]
	v_pk_fma_f32 v[90:91], v[90:91], v[98:99], v[82:83] op_sel_hi:[1,0,1]
	s_cbranch_vccnz .LBB0_606
	v_max_f32_e32 v94, 0, v94
	v_max_f32_e32 v90, 0, v90
	v_max_f32_e32 v95, 0, v95
	v_max_f32_e32 v91, 0, v91
	v_max_f32_e32 v96, 0, v96
	v_max_f32_e32 v92, 0, v92
	v_max_f32_e32 v97, 0, v97
	v_max_f32_e32 v93, 0, v93
	v_pk_mul_f32 v[94:95], v[94:95], v[94:95]
	v_pk_mul_f32 v[96:97], v[96:97], v[96:97]
	v_pk_mul_f32 v[90:91], v[90:91], v[90:91]
	v_pk_mul_f32 v[92:93], v[92:93], v[92:93]

.LBB0_609:
	v_mov_b32_e32 v99, v98
	v_mov_b32_e32 v90, v98
	v_mov_b32_e32 v91, v98
	v_pk_fma_f32 v[80:81], v[80:81], v[90:91], v[72:73]
	v_pk_fma_f32 v[78:79], v[78:79], v[98:99], v[70:71]
	v_pk_fma_f32 v[76:77], v[76:77], v[90:91], v[68:69]
	s_and_b64 vcc, exec, s[42:43]
	v_pk_fma_f32 v[74:75], v[74:75], v[98:99], v[66:67]
	s_cbranch_vccnz .LBB0_611
	v_max_f32_e32 v78, 0, v78
	v_max_f32_e32 v74, 0, v74
	v_max_f32_e32 v79, 0, v79
	v_max_f32_e32 v75, 0, v75
	v_max_f32_e32 v80, 0, v80
	v_max_f32_e32 v76, 0, v76
	v_max_f32_e32 v81, 0, v81
	v_max_f32_e32 v77, 0, v77
	v_pk_mul_f32 v[78:79], v[78:79], v[78:79]
	v_pk_mul_f32 v[80:81], v[80:81], v[80:81]
	v_pk_mul_f32 v[74:75], v[74:75], v[74:75]
	v_pk_mul_f32 v[76:77], v[76:77], v[76:77]

.LBB0_614:
	ds_bpermute_b32 v74, v175, v163
	s_and_b64 vcc, exec, s[42:43]
	s_waitcnt lgkmcnt(0)
	v_pk_fma_f32 v[64:65], v[64:65], v[74:75], v[88:89] op_sel_hi:[1,0,1]
	v_pk_fma_f32 v[62:63], v[62:63], v[74:75], v[86:87] op_sel_hi:[1,0,1]
	v_pk_fma_f32 v[60:61], v[60:61], v[74:75], v[84:85] op_sel_hi:[1,0,1]
	v_pk_fma_f32 v[58:59], v[58:59], v[74:75], v[82:83] op_sel_hi:[1,0,1]
	s_cbranch_vccnz .LBB0_616
	v_max_f32_e32 v62, 0, v62
	v_max_f32_e32 v58, 0, v58
	v_max_f32_e32 v63, 0, v63
	v_max_f32_e32 v59, 0, v59
	v_max_f32_e32 v64, 0, v64
	v_max_f32_e32 v60, 0, v60
	v_max_f32_e32 v65, 0, v65
	v_max_f32_e32 v61, 0, v61
	v_pk_mul_f32 v[62:63], v[62:63], v[62:63]
	v_pk_mul_f32 v[64:65], v[64:65], v[64:65]
	v_pk_mul_f32 v[58:59], v[58:59], v[58:59]
	v_pk_mul_f32 v[60:61], v[60:61], v[60:61]

.LBB0_619:
	v_mov_b32_e32 v75, v74
	v_mov_b32_e32 v58, v74
	v_mov_b32_e32 v59, v74
	v_pk_fma_f32 v[56:57], v[56:57], v[58:59], v[72:73]
	v_pk_fma_f32 v[54:55], v[54:55], v[74:75], v[70:71]
	v_pk_fma_f32 v[52:53], v[52:53], v[58:59], v[68:69]
	s_and_b64 vcc, exec, s[42:43]
	v_pk_fma_f32 v[50:51], v[50:51], v[74:75], v[66:67]
	s_cbranch_vccnz .LBB0_621
	v_max_f32_e32 v54, 0, v54
	v_max_f32_e32 v50, 0, v50
	v_max_f32_e32 v55, 0, v55
	v_max_f32_e32 v51, 0, v51
	v_max_f32_e32 v56, 0, v56
	v_max_f32_e32 v52, 0, v52
	v_max_f32_e32 v57, 0, v57
	v_max_f32_e32 v53, 0, v53
	v_pk_mul_f32 v[54:55], v[54:55], v[54:55]
	v_pk_mul_f32 v[56:57], v[56:57], v[56:57]
	v_pk_mul_f32 v[50:51], v[50:51], v[50:51]
	v_pk_mul_f32 v[52:53], v[52:53], v[52:53]

.LBB0_624:
	s_nop 0
	v_or_b32_e32 v50, 64, v175
	ds_bpermute_b32 v50, v50, v163
	s_and_b64 vcc, exec, s[42:43]
	s_waitcnt lgkmcnt(0)
	v_pk_fma_f32 v[48:49], v[48:49], v[50:51], v[88:89] op_sel_hi:[1,0,1]
	v_pk_fma_f32 v[46:47], v[46:47], v[50:51], v[86:87] op_sel_hi:[1,0,1]
	v_pk_fma_f32 v[44:45], v[44:45], v[50:51], v[84:85] op_sel_hi:[1,0,1]
	v_pk_fma_f32 v[42:43], v[42:43], v[50:51], v[82:83] op_sel_hi:[1,0,1]
	s_cbranch_vccnz .LBB0_626
	v_max_f32_e32 v46, 0, v46
	v_max_f32_e32 v42, 0, v42
	v_max_f32_e32 v47, 0, v47
	v_max_f32_e32 v43, 0, v43
	v_max_f32_e32 v48, 0, v48
	v_max_f32_e32 v44, 0, v44
	v_max_f32_e32 v49, 0, v49
	v_max_f32_e32 v45, 0, v45
	v_pk_mul_f32 v[46:47], v[46:47], v[46:47]
	v_pk_mul_f32 v[48:49], v[48:49], v[48:49]
	v_pk_mul_f32 v[42:43], v[42:43], v[42:43]
	v_pk_mul_f32 v[44:45], v[44:45], v[44:45]

.LBB0_629:
	v_mov_b32_e32 v51, v50
	v_mov_b32_e32 v42, v50
	v_mov_b32_e32 v43, v50
	v_pk_fma_f32 v[40:41], v[40:41], v[42:43], v[72:73]
	v_pk_fma_f32 v[38:39], v[38:39], v[50:51], v[70:71]
	v_pk_fma_f32 v[36:37], v[36:37], v[42:43], v[68:69]
	s_and_b64 vcc, exec, s[42:43]
	v_pk_fma_f32 v[34:35], v[34:35], v[50:51], v[66:67]
	s_cbranch_vccnz .LBB0_631
	v_max_f32_e32 v38, 0, v38
	v_max_f32_e32 v34, 0, v34
	v_max_f32_e32 v39, 0, v39
	v_max_f32_e32 v35, 0, v35
	v_max_f32_e32 v40, 0, v40
	v_max_f32_e32 v36, 0, v36
	v_max_f32_e32 v41, 0, v41
	v_max_f32_e32 v37, 0, v37
	v_pk_mul_f32 v[38:39], v[38:39], v[38:39]
	v_pk_mul_f32 v[40:41], v[40:41], v[40:41]
	v_pk_mul_f32 v[34:35], v[34:35], v[34:35]
	v_pk_mul_f32 v[36:37], v[36:37], v[36:37]

.LBB0_634:
	s_nop 0
	v_or_b32_e32 v34, 0x80, v175
	ds_bpermute_b32 v34, v34, v163
	s_and_b64 vcc, exec, s[42:43]
	s_waitcnt lgkmcnt(0)
	v_pk_fma_f32 v[30:31], v[30:31], v[34:35], v[88:89] op_sel_hi:[1,0,1]
	v_pk_fma_f32 v[28:29], v[28:29], v[34:35], v[86:87] op_sel_hi:[1,0,1]
	v_pk_fma_f32 v[26:27], v[26:27], v[34:35], v[84:85] op_sel_hi:[1,0,1]
	v_pk_fma_f32 v[24:25], v[24:25], v[34:35], v[82:83] op_sel_hi:[1,0,1]
	s_cbranch_vccnz .LBB0_636
	v_max_f32_e32 v28, 0, v28
	v_max_f32_e32 v24, 0, v24
	v_max_f32_e32 v29, 0, v29
	v_max_f32_e32 v25, 0, v25
	v_max_f32_e32 v30, 0, v30
	v_max_f32_e32 v26, 0, v26
	v_max_f32_e32 v31, 0, v31
	v_max_f32_e32 v27, 0, v27
	v_pk_mul_f32 v[28:29], v[28:29], v[28:29]
	v_pk_mul_f32 v[30:31], v[30:31], v[30:31]
	v_pk_mul_f32 v[24:25], v[24:25], v[24:25]
	v_pk_mul_f32 v[26:27], v[26:27], v[26:27]

.LBB0_639:
	v_mov_b32_e32 v35, v34
	v_mov_b32_e32 v24, v34
	v_mov_b32_e32 v25, v34
	v_pk_fma_f32 v[22:23], v[22:23], v[24:25], v[72:73]
	v_pk_fma_f32 v[20:21], v[20:21], v[34:35], v[70:71]
	v_pk_fma_f32 v[18:19], v[18:19], v[24:25], v[68:69]
	s_and_b64 vcc, exec, s[42:43]
	v_pk_fma_f32 v[16:17], v[16:17], v[34:35], v[66:67]
	s_cbranch_vccnz .LBB0_641
	v_max_f32_e32 v20, 0, v20
	v_max_f32_e32 v16, 0, v16
	v_max_f32_e32 v21, 0, v21
	v_max_f32_e32 v17, 0, v17
	v_max_f32_e32 v22, 0, v22
	v_max_f32_e32 v18, 0, v18
	v_max_f32_e32 v23, 0, v23
	v_max_f32_e32 v19, 0, v19
	v_pk_mul_f32 v[20:21], v[20:21], v[20:21]
	v_pk_mul_f32 v[22:23], v[22:23], v[22:23]
	v_pk_mul_f32 v[16:17], v[16:17], v[16:17]
	v_pk_mul_f32 v[18:19], v[18:19], v[18:19]

.LBB0_644:
	s_nop 0
	v_or_b32_e32 v16, 0xc0, v175
	ds_bpermute_b32 v16, v16, v163
	s_and_b64 vcc, exec, s[42:43]
	s_waitcnt lgkmcnt(0)
	v_pk_fma_f32 v[14:15], v[14:15], v[16:17], v[88:89] op_sel_hi:[1,0,1]
	v_pk_fma_f32 v[12:13], v[12:13], v[16:17], v[86:87] op_sel_hi:[1,0,1]
	v_pk_fma_f32 v[10:11], v[10:11], v[16:17], v[84:85] op_sel_hi:[1,0,1]
	v_pk_fma_f32 v[8:9], v[8:9], v[16:17], v[82:83] op_sel_hi:[1,0,1]
	s_cbranch_vccnz .LBB0_646
	v_max_f32_e32 v12, 0, v12
	v_max_f32_e32 v8, 0, v8
	v_max_f32_e32 v13, 0, v13
	v_max_f32_e32 v9, 0, v9
	v_max_f32_e32 v14, 0, v14
	v_max_f32_e32 v10, 0, v10
	v_max_f32_e32 v15, 0, v15
	v_max_f32_e32 v11, 0, v11
	v_pk_mul_f32 v[12:13], v[12:13], v[12:13]
	v_pk_mul_f32 v[14:15], v[14:15], v[14:15]
	v_pk_mul_f32 v[8:9], v[8:9], v[8:9]
	v_pk_mul_f32 v[10:11], v[10:11], v[10:11]

.LBB0_649:
	v_mov_b32_e32 v17, v16
	v_mov_b32_e32 v8, v16
	v_mov_b32_e32 v9, v16
	v_pk_fma_f32 v[6:7], v[6:7], v[8:9], v[72:73]
	v_pk_fma_f32 v[4:5], v[4:5], v[16:17], v[70:71]
	v_pk_fma_f32 v[2:3], v[2:3], v[8:9], v[68:69]
	s_and_b64 vcc, exec, s[42:43]
	v_pk_fma_f32 v[0:1], v[0:1], v[16:17], v[66:67]
	s_cbranch_vccnz .LBB0_651
	v_max_f32_e32 v4, 0, v4
	v_max_f32_e32 v0, 0, v0
	v_max_f32_e32 v5, 0, v5
	v_max_f32_e32 v1, 0, v1
	v_max_f32_e32 v6, 0, v6
	v_max_f32_e32 v2, 0, v2
	v_max_f32_e32 v7, 0, v7
	v_max_f32_e32 v3, 0, v3
	v_pk_mul_f32 v[4:5], v[4:5], v[4:5]
	v_pk_mul_f32 v[6:7], v[6:7], v[6:7]
	v_pk_mul_f32 v[0:1], v[0:1], v[0:1]
	v_pk_mul_f32 v[2:3], v[2:3], v[2:3]
